# ret_kv units rebalanced between CUs with/without an S5 chunk-state GEMM unit; accumulator zeroing as 64-bit moves
# speedup vs baseline: 1.0218x; 1.0118x over previous
;     __device__ __forceinline__ bool next(int i, Unit& u) const { const int L = i * G + c; if (L >= nM * nN * ng) return false; const int per = nM * nN, r = L % per; u.g = L / per; u.pn = r / nM; u.pm = r % nM; return true; }
; template <class Epi, class Sched, bool ALIGN_EPI = false, bool SP2 = false>
; __device__ __forceinline__ void gemm_phase(PG8_LAS unsigned char* lds, const Gemm g, const Sched& S, const Epi& E) {
;     ...
;         const bool has_next = S.next(ui + 1, nxt);
;         const char* nA = has_next ? (const char*)g.A + (size_t)nxt.g * g.gsA * 2 + (size_t)nxt.pm * tstepA : cA; const char* nB = has_next ? (const char*)g.Bt + (size_t)nxt.g * g.gsB * 2 + (size_t)nxt.pn * tstepB : cB;
;         for (int t = 0; t < nt; t += 2) {
;             const bool last = (t == nt - 2);
;             const char* a1 = cA + (size_t)(t + 1) * kstep;
;             const char* a2 = last ? nA : cA + (size_t)(t + 2) * kstep; const char* b2 = last ? nB : cB + (size_t)(t + 2) * kstep;
;             const char* a3 = a2 + kstep; const char* b3 = b2 + kstep;
;     ...
; #pragma unroll
;         for (int a = 0; a < 2; ++a)
; #pragma unroll
;             for (int b = 0; b < 2; ++b)
; #pragma unroll
;                 for (int m = 0; m < 4; ++m)
; #pragma unroll
;                     for (int n = 0; n < 2; ++n) acc[a][b][m][n] = (f32x4){0.f, 0.f, 0.f, 0.f};
.LBB0_196:
	s_ashr_i32 s21, s20, 31
	s_lshl_b64 s[22:23], s[20:21], 19
	s_add_u32 s22, s3, s22
	s_addc_u32 s23, s34, s23
	s_and_b64 s[24:25], s[6:7], exec
	s_cselect_b32 s1, s23, s27
	s_cselect_b32 s2, s22, s26
	s_ashr_i32 s19, s18, 31
	s_lshl_b64 s[24:25], s[18:19], 19
	s_add_u32 s24, s35, s24
	s_addc_u32 s25, s36, s25
	s_and_b64 s[30:31], s[6:7], exec
	s_cselect_b32 s5, s25, s29
	s_cselect_b32 s19, s24, s28
	s_add_u32 s26, s26, 0x40080
	s_addc_u32 s27, s27, 0
	s_add_u32 s21, s28, 0x100
	v_mov_b64_e32 v[2:3], 0
	v_mov_b64_e32 v[4:5], 0
	v_mov_b64_e32 v[6:7], 0
	v_mov_b64_e32 v[8:9], 0
	v_mov_b64_e32 v[10:11], 0
	v_mov_b64_e32 v[12:13], 0
	v_mov_b64_e32 v[14:15], 0
	v_mov_b64_e32 v[16:17], 0
	v_mov_b64_e32 v[18:19], 0
	v_mov_b64_e32 v[20:21], 0
	v_mov_b64_e32 v[22:23], 0
	v_mov_b64_e32 v[24:25], 0
	v_mov_b64_e32 v[26:27], 0
	v_mov_b64_e32 v[28:29], 0
	v_mov_b64_e32 v[30:31], 0
	v_mov_b64_e32 v[32:33], 0
	v_mov_b64_e32 v[34:35], 0
	v_mov_b64_e32 v[36:37], 0
	v_mov_b64_e32 v[38:39], 0
	v_mov_b64_e32 v[40:41], 0
	v_mov_b64_e32 v[42:43], 0
	v_mov_b64_e32 v[44:45], 0
	v_mov_b64_e32 v[46:47], 0
	v_mov_b64_e32 v[48:49], 0
	v_mov_b64_e32 v[50:51], 0
	v_mov_b64_e32 v[52:53], 0
	v_mov_b64_e32 v[54:55], 0
	v_mov_b64_e32 v[56:57], 0
	v_mov_b64_e32 v[58:59], 0
	v_mov_b64_e32 v[60:61], 0
	v_mov_b64_e32 v[62:63], 0
	v_mov_b64_e32 v[64:65], 0
	v_mov_b64_e32 v[66:67], 0
	v_mov_b64_e32 v[68:69], 0
	v_mov_b64_e32 v[70:71], 0
	v_mov_b64_e32 v[72:73], 0
	v_mov_b64_e32 v[74:75], 0
	v_mov_b64_e32 v[76:77], 0
	v_mov_b64_e32 v[78:79], 0
	v_mov_b64_e32 v[80:81], 0
	v_mov_b64_e32 v[82:83], 0
	v_mov_b64_e32 v[84:85], 0
	v_mov_b64_e32 v[86:87], 0
	v_mov_b64_e32 v[88:89], 0
	v_mov_b64_e32 v[90:91], 0
	v_mov_b64_e32 v[92:93], 0
	v_mov_b64_e32 v[94:95], 0
	v_mov_b64_e32 v[96:97], 0
	v_mov_b64_e32 v[98:99], 0
	v_mov_b64_e32 v[100:101], 0
	v_mov_b64_e32 v[102:103], 0
	v_mov_b64_e32 v[104:105], 0
	v_mov_b64_e32 v[106:107], 0
	v_mov_b64_e32 v[108:109], 0
	v_mov_b64_e32 v[110:111], 0
	v_mov_b64_e32 v[112:113], 0
	v_mov_b64_e32 v[114:115], 0
	v_mov_b64_e32 v[116:117], 0
	v_mov_b64_e32 v[118:119], 0
	v_mov_b64_e32 v[120:121], 0
	v_mov_b64_e32 v[122:123], 0
	v_mov_b64_e32 v[124:125], 0
	v_mov_b64_e32 v[126:127], 0
	v_mov_b64_e32 v[128:129], 0
	s_addc_u32 s33, s29, 0
	s_mov_b32 s60, -2
	s_waitcnt lgkmcnt(0)

; #define LAS __attribute__((address_space(3)))
; __device__ __forceinline__ float ret_log2g(int h) { return log1pf(-exp2f(-5.f - (float)h)) * 1.4426950408889634f; }
; #define PUTK(k, w) kd[(k) * VT_LD] = (bf16)f2bf(bflo(w) * z); kd[((k) + 1) * VT_LD] = (bf16)f2bf(bfhi(w) * z)
; __device__ __forceinline__ void ret_kv_phase(const Frame& F, const bf16* P0, float* KV) {
;     LAS bf16* Vt = (LAS bf16*)F.lds; LAS bf16* Kt = Vt + 64 * VT_LD;
;     const int fr = F.lane & 15, fq = F.lane >> 4; const int s = F.tid >> 2, part = F.tid & 3;
;     v4u pv0, pv1, pk0, pk1;
;     ...
;     int u = F.bx; if (u < 2048) KV_PREFETCH(u);
;     for (; u < 2048; u += F.G) { const int h = (u >> 5) & 7; const float lg = ret_log2g(h);
;         __syncthreads();
;         { LAS bf16* vd = Vt + (16 * part) * VT_LD + s; LAS bf16* kd = Kt + (16 * part) * VT_LD + s; const float z = exp2f((float)(127 - s) * lg);
;     ...
;           PUT(0, pv0.x); PUT(2, pv0.y); PUT(4, pv0.z); PUT(6, pv0.w); PUT(8, pv1.x); PUT(10, pv1.y); PUT(12, pv1.z); PUT(14, pv1.w);
;           PUTK(0, pk0.x); PUTK(2, pk0.y); PUTK(4, pk0.z); PUTK(6, pk0.w); PUTK(8, pk1.x); PUTK(10, pk1.y); PUTK(12, pk1.z); PUTK(14, pk1.w);
;     ...
;         }
;         __syncthreads();
;         if (u + F.G < 2048) KV_PREFETCH(u + F.G);
; #pragma unroll
;         for (int t2 = 0; t2 < 2; ++t2) { const int id = 2 * F.wave + t2, et = id >> 2, dt = id & 3; pg8::f32x4 acc = {0.f, 0.f, 0.f, 0.f};
.LBB0_287:
	s_mov_b32 s99, s96
	s_mov_b32 s100, s82
	s_and_b32 s98, s96, 7
	s_lshr_b32 s101, s96, 3
	s_cmp_lt_u32 s98, 4
	s_cbranch_scc0 .Lmy_kvB
	s_lshl_b32 s98, s98, 5
	s_add_i32 s96, s98, s101
	s_movk_i32 s98, 0x200
	s_branch .Lmy_kvJ
.Lmy_kvB:
	s_sub_i32 s98, s98, 4
	s_lshl_b32 s98, s98, 5
	s_add_i32 s96, s98, s101
	s_addk_i32 s96, 0x200
	s_movk_i32 s98, 0x800
.Lmy_kvJ:
	s_movk_i32 s82, 0x80
	v_mov_b32_e32 v20, v0
	s_cmp_ge_i32 s96, s98
	v_readfirstlane_b32 s0, v20
	s_cbranch_scc1 .LBB0_292
	s_add_u32 s4, s78, 0x13c00000
	s_addc_u32 s5, s79, 0
	s_lshl_b32 s1, s96, 4
	s_lshl_b32 s2, s96, 7
	s_and_b32 s1, s1, 0xfffff000
	s_and_b32 s2, s2, 0xf80
	v_ashrrev_i32_e32 v1, 2, v20
	s_or_b32 s1, s1, s2
	v_add_u32_e32 v2, s1, v1
	v_ashrrev_i32_e32 v3, 31, v2
	v_lshlrev_b64 v[2:3], 12, v[2:3]
	s_lshl_b32 s1, s96, 2
	v_and_b32_e32 v21, 3, v20
	v_lshl_add_u64 v[2:3], s[4:5], 0, v[2:3]
	s_and_b32 s6, s1, 0x380
	s_mov_b32 s7, 0
	v_lshl_add_u64 v[2:3], v[2:3], 0, s[6:7]
	v_mov_b32_e32 v19, 0
	v_lshlrev_b32_e32 v18, 5, v21
	v_lshl_add_u64 v[22:23], v[2:3], 0, v[18:19]
	global_load_dwordx4 v[2:5], v[22:23], off offset:2048
	global_load_dwordx4 v[6:9], v[22:23], off offset:2064
	global_load_dwordx4 v[10:13], v[22:23], off offset:1040
	global_load_dwordx4 v[14:17], v[22:23], off offset:1024
	v_and_b32_e32 v26, 15, v20
	v_bfe_u32 v20, v20, 4, 2
	s_ashr_i32 s1, s0, 7
	v_lshl_add_u32 v28, v20, 4, 0
	v_lshlrev_b32_e32 v24, 8, v20
	v_lshl_or_b32 v20, s1, 4, v26
	s_movk_i32 s2, 0x110
	v_lshlrev_b32_e32 v18, 4, v21
	v_mul_u32_u24_e32 v21, 0x880, v21
	v_mul_lo_u32 v27, v20, s2
	s_lshr_b32 s2, s0, 1
	s_ashr_i32 s97, s96, 31
	s_lshl_b32 s0, s0, 1
	v_lshlrev_b32_e32 v22, 1, v1
	v_lshlrev_b32_e32 v21, 1, v21
	v_and_or_b32 v20, s2, 32, v26
	s_lshl_b64 s[2:3], s[96:97], 14
	s_and_b32 s0, s0, 0x80
	v_add3_u32 v22, 0, v22, v21
	v_sub_u32_e32 v21, 0x7f, v1
	v_mul_u32_u24_e32 v29, 0x110, v20
	v_or_b32_e32 v20, 16, v20
	s_or_b32 s0, s2, s0
	v_lshl_or_b32 v24, s1, 10, v24
	v_cvt_f32_i32_e32 v23, v21
	v_mul_u32_u24_e32 v30, 0x110, v20
	v_mov_b32_e32 v20, s0
	v_mov_b32_e32 v21, s3
	v_ashrrev_i32_e32 v25, 31, v24
	v_lshl_add_u64 v[20:21], v[24:25], 2, v[20:21]
	v_lshl_or_b32 v20, v26, 2, v20
	v_lshl_add_u64 v[20:21], s[78:79], 0, v[20:21]
	s_mov_b64 s[0:1], 0xbc00200
	v_lshl_add_u64 v[20:21], v[20:21], 0, s[0:1]
	s_ashr_i32 s1, s82, 31
	s_mov_b32 s0, s82
	s_add_i32 s6, s96, s82
	s_lshl_b64 s[8:9], s[0:1], 14
	s_lshl_b32 s0, s6, 1
	s_lshl_b32 s1, s82, 1
	s_lshl_b32 s2, s6, 7
	s_lshl_b32 s3, s82, 7
	s_lshl_b32 s12, s6, 4
	s_lshl_b32 s13, s82, 4
	s_mov_b32 s14, 0xc2fc0000
	v_mov_b32_e32 v24, 0x42800000
	s_mov_b32 s15, 0x3f2aaaab
	v_mov_b32_e32 v25, 0x3ecc95a3
	s_mov_b32 s16, 0x3f317218
	s_mov_b32 s17, 0x33800000
	s_movk_i32 s18, 0x7fff
	v_lshlrev_b32_e32 v18, 1, v18
	v_add_u32_e32 v26, v28, v27
	v_add_u32_e32 v27, v28, v29
	v_add_u32_e32 v28, v28, v30
	v_mov_b32_e32 v29, 0x7fc00000
	v_mov_b32_e32 v30, 0xff800000
	v_not_b32_e32 v31, 63
	s_mov_b32 s19, s96
	s_branch .LBB0_290

; #define LAS __attribute__((address_space(3)))
; #define PUTK(k, w) kd[(k) * VT_LD] = (bf16)f2bf(bflo(w) * z); kd[((k) + 1) * VT_LD] = (bf16)f2bf(bfhi(w) * z)
; __device__ __forceinline__ float ret_log2g(int h) { return log1pf(-exp2f(-5.f - (float)h)) * 1.4426950408889634f; }
; __device__ __forceinline__ void ret_kv_phase(const Frame& F, const bf16* P0, float* KV) {
;     ...
;     for (; u < 2048; u += F.G) { const int h = (u >> 5) & 7; const float lg = ret_log2g(h);
;         __syncthreads();
;         { LAS bf16* vd = Vt + (16 * part) * VT_LD + s; LAS bf16* kd = Kt + (16 * part) * VT_LD + s; const float z = exp2f((float)(127 - s) * lg);
;     ...
;           PUT(0, pv0.x); PUT(2, pv0.y); PUT(4, pv0.z); PUT(6, pv0.w); PUT(8, pv1.x); PUT(10, pv1.y); PUT(12, pv1.z); PUT(14, pv1.w);
;           PUTK(0, pk0.x); PUTK(2, pk0.y); PUTK(4, pk0.z); PUTK(6, pk0.w); PUTK(8, pk1.x); PUTK(10, pk1.y); PUTK(12, pk1.z); PUTK(14, pk1.w);
.LBB0_290:
	s_bfe_u32 s6, s19, 0x30005
	v_cvt_f32_ubyte0_e32 v32, s6
	v_sub_f32_e32 v32, 0xc0a00000, v32
	v_cmp_gt_f32_e32 vcc, s14, v32
	s_and_b64 s[10:11], vcc, exec
	s_cselect_b32 s6, 0xffffffc0, 0
	v_cndmask_b32_e32 v33, 0, v24, vcc
	v_add_f32_e32 v32, v32, v33
	v_exp_f32_e32 v32, v32
	s_waitcnt vmcnt(0) lgkmcnt(0)
	s_barrier
	v_ldexp_f32 v34, v32, s6
	v_sub_f32_e32 v35, 1.0, v34
	v_add_f32_e32 v32, -1.0, v35
	v_sub_f32_e32 v33, v32, v35
	v_add_f32_e32 v33, 1.0, v33
	v_sub_f32_e64 v32, -v34, v32
	v_add_f32_e32 v36, v32, v33
	v_frexp_mant_f32_e32 v37, v35
	v_cvt_f64_f32_e32 v[32:33], v35
	v_frexp_exp_i32_f64_e32 v32, v[32:33]
	v_cmp_gt_f32_e32 vcc, s15, v37
	ds_write_b16 v22, v2
	ds_write_b16_d16_hi v22, v2 offset:272
	ds_write_b16 v22, v3 offset:544
	ds_write_b16_d16_hi v22, v3 offset:816
	ds_write_b16 v22, v4 offset:1088
	ds_write_b16_d16_hi v22, v4 offset:1360
	ds_write_b16 v22, v5 offset:1632
	ds_write_b16_d16_hi v22, v5 offset:1904
	ds_write_b16 v22, v6 offset:2176
	ds_write_b16_d16_hi v22, v6 offset:2448
	ds_write_b16 v22, v7 offset:2720
	ds_write_b16_d16_hi v22, v7 offset:2992
	ds_write_b16 v22, v8 offset:3264
	ds_write_b16_d16_hi v22, v8 offset:3536
	ds_write_b16 v22, v9 offset:3808
	ds_write_b16_d16_hi v22, v9 offset:4080
	v_subbrev_co_u32_e32 v32, vcc, 0, v32, vcc
	v_sub_u32_e32 v33, 0, v32
	v_ldexp_f32 v35, v35, v33
	v_ldexp_f32 v33, v36, v33
	v_add_f32_e32 v36, -1.0, v35
	v_add_f32_e32 v39, 1.0, v35
	v_add_f32_e32 v37, 1.0, v36
	v_add_f32_e32 v40, -1.0, v39
	v_sub_f32_e32 v37, v35, v37
	v_sub_f32_e32 v35, v35, v40
	v_add_f32_e32 v37, v33, v37
	v_add_f32_e32 v33, v33, v35
	v_add_f32_e32 v35, v39, v33
	v_rcp_f32_e32 v40, v35
	v_add_f32_e32 v38, v36, v37
	v_sub_f32_e32 v36, v38, v36
	v_sub_f32_e32 v36, v37, v36
	v_sub_f32_e32 v37, v35, v39
	v_sub_f32_e32 v33, v33, v37
	v_mul_f32_e32 v37, v38, v40
	v_mul_f32_e32 v39, v35, v37
	v_fma_f32 v41, v37, v35, -v39
	v_fmac_f32_e32 v41, v37, v33
	v_add_f32_e32 v42, v39, v41
	v_sub_f32_e32 v43, v38, v42
	v_sub_f32_e32 v38, v38, v43
	v_sub_f32_e32 v39, v42, v39
	v_sub_f32_e32 v38, v38, v42
	v_add_f32_e32 v36, v36, v38
	v_sub_f32_e32 v38, v39, v41
	v_add_f32_e32 v36, v38, v36
	v_add_f32_e32 v38, v43, v36
	v_mul_f32_e32 v39, v40, v38
	v_mul_f32_e32 v41, v35, v39
	v_fma_f32 v35, v39, v35, -v41
	v_fmac_f32_e32 v35, v39, v33
	v_sub_f32_e32 v33, v43, v38
	v_add_f32_e32 v33, v36, v33
	v_add_f32_e32 v36, v41, v35
	v_sub_f32_e32 v42, v38, v36
	v_sub_f32_e32 v38, v38, v42
	v_sub_f32_e32 v41, v36, v41
	v_sub_f32_e32 v36, v38, v36
	v_add_f32_e32 v33, v33, v36
	v_sub_f32_e32 v35, v41, v35
	v_cvt_f32_i32_e32 v32, v32
	v_add_f32_e32 v33, v35, v33
	v_add_f32_e32 v35, v37, v39
	v_add_f32_e32 v33, v42, v33
	v_sub_f32_e32 v36, v35, v37
	v_mul_f32_e32 v33, v40, v33
	v_sub_f32_e32 v36, v39, v36
	v_add_f32_e32 v33, v36, v33
	v_mul_f32_e32 v39, 0x3f317218, v32
	v_add_f32_e32 v36, v35, v33
	v_fma_f32 v40, v32, s16, -v39
	v_mul_f32_e32 v37, v36, v36
	v_fmac_f32_e32 v40, 0xb102e308, v32
	v_sub_f32_e32 v32, v36, v35
	v_fmamk_f32 v38, v37, 0x3e9b6dac, v25
	v_sub_f32_e32 v32, v33, v32
	v_add_f32_e32 v33, v39, v40
	v_fmaak_f32 v38, v37, v38, 0x3f2aaada
	v_sub_f32_e32 v35, v33, v39
	v_ldexp_f32 v39, v36, 1
	v_mul_f32_e32 v36, v36, v37
	v_mul_f32_e32 v36, v36, v38
	v_add_f32_e32 v37, v39, v36
	v_sub_f32_e32 v38, v37, v39
	v_ldexp_f32 v32, v32, 1
	v_sub_f32_e32 v36, v36, v38
	v_add_f32_e32 v32, v32, v36
	v_add_f32_e32 v36, v37, v32
	v_sub_f32_e32 v37, v36, v37
	v_sub_f32_e32 v32, v32, v37
	v_add_f32_e32 v37, v33, v36
	v_sub_f32_e32 v38, v37, v33
	v_sub_f32_e32 v39, v37, v38
	v_sub_f32_e32 v35, v40, v35
	v_sub_f32_e32 v33, v33, v39
	v_sub_f32_e32 v36, v36, v38
	v_add_f32_e32 v33, v36, v33
	v_add_f32_e32 v36, v35, v32
	v_sub_f32_e32 v38, v36, v35
	v_sub_f32_e32 v39, v36, v38
	v_sub_f32_e32 v35, v35, v39
	v_sub_f32_e32 v32, v32, v38
	v_add_f32_e32 v33, v36, v33
	v_add_f32_e32 v32, v32, v35
	v_add_f32_e32 v35, v37, v33
	v_sub_f32_e32 v36, v35, v37
	v_sub_f32_e32 v33, v33, v36
	v_add_f32_e32 v32, v32, v33
	v_add_f32_e32 v32, v35, v32
	v_cmp_nlt_f32_e32 vcc, 1.0, v34
	s_add_i32 s19, s19, s82
	s_cmp_ge_i32 s19, s98
	v_cndmask_b32_e32 v32, v29, v32, vcc
	v_cmp_neq_f32_e32 vcc, 1.0, v34
	s_cselect_b64 s[10:11], -1, 0
	s_nop 0
	v_cndmask_b32_e32 v32, v30, v32, vcc
	v_cmp_gt_f32_e32 vcc, s17, v34
	s_nop 1
	v_cndmask_b32_e64 v32, v32, -v34, vcc
	v_mul_f32_e32 v32, 0x3fb8aa3b, v32
	v_mul_f32_e32 v33, v32, v23
	v_cmp_gt_f32_e32 vcc, s14, v33
	s_nop 1
	v_cndmask_b32_e32 v33, 0, v24, vcc
	v_fmac_f32_e32 v33, v32, v23
	v_exp_f32_e32 v32, v33
	v_cndmask_b32_e32 v33, 0, v31, vcc
	s_and_b64 vcc, exec, s[10:11]
	v_ldexp_f32 v32, v32, v33
	v_lshlrev_b32_e32 v33, 16, v14
	v_mul_f32_e32 v33, v32, v33
	v_bfe_u32 v34, v33, 16, 1
	v_add3_u32 v33, v33, v34, s18
; __device__ __forceinline__ unsigned xb_add(unsigned* p, unsigned v) { return __hip_atomic_fetch_add(p, v, __ATOMIC_RELAXED, __HIP_MEMORY_SCOPE_AGENT); }
; #define PUTK(k, w) kd[(k) * VT_LD] = (bf16)f2bf(bflo(w) * z); kd[((k) + 1) * VT_LD] = (bf16)f2bf(bfhi(w) * z)
; __device__ __forceinline__ void xcd_barrier(const XcdBarrier& b) {
;     asm volatile("s_waitcnt vmcnt(0)" ::: "memory");
;     __syncthreads();
;     if (threadIdx.x == 0) {
;         unsigned* bar = b.bar;
;         __builtin_amdgcn_s_waitcnt(0);
;         unsigned nloc = b.st[0], nx = b.st[1];
;         if (nloc == 0u) { xcd_barrier_complete(bar, b.x, nloc, nx); b.st[0] = nloc; b.st[1] = nx; }
;         const unsigned old = xb_add(&bar[XB_XSUB(b.x)], 1u);
; __device__ __forceinline__ void ret_kv_phase(const Frame& F, const bf16* P0, float* KV) {
;     ...
;           PUTK(0, pk0.x); PUTK(2, pk0.y); PUTK(4, pk0.z); PUTK(6, pk0.w); PUTK(8, pk1.x); PUTK(10, pk1.y); PUTK(12, pk1.z); PUTK(14, pk1.w);
;     ...
;         }
;         __syncthreads();
;         if (u + F.G < 2048) KV_PREFETCH(u + F.G);
	ds_write_b16_d16_hi v22, v33 offset:17408
	v_and_b32_e32 v33, 0xffff0000, v14
	v_mul_f32_e32 v33, v32, v33
	v_bfe_u32 v34, v33, 16, 1
	v_add3_u32 v33, v33, v34, s18
	ds_write_b16_d16_hi v22, v33 offset:17680
	v_lshlrev_b32_e32 v33, 16, v15
	v_mul_f32_e32 v33, v32, v33
	v_bfe_u32 v34, v33, 16, 1
	v_add3_u32 v33, v33, v34, s18
	ds_write_b16_d16_hi v22, v33 offset:17952
	v_and_b32_e32 v33, 0xffff0000, v15
	v_mul_f32_e32 v33, v32, v33
	v_bfe_u32 v34, v33, 16, 1
	v_add3_u32 v33, v33, v34, s18
	ds_write_b16_d16_hi v22, v33 offset:18224
	v_lshlrev_b32_e32 v33, 16, v16
	v_mul_f32_e32 v33, v32, v33
	v_bfe_u32 v34, v33, 16, 1
	v_add3_u32 v33, v33, v34, s18
	ds_write_b16_d16_hi v22, v33 offset:18496
	v_and_b32_e32 v33, 0xffff0000, v16
	v_mul_f32_e32 v33, v32, v33
	v_bfe_u32 v34, v33, 16, 1
	v_add3_u32 v33, v33, v34, s18
	ds_write_b16_d16_hi v22, v33 offset:18768
	v_lshlrev_b32_e32 v33, 16, v17
	v_mul_f32_e32 v33, v32, v33
	v_bfe_u32 v34, v33, 16, 1
	v_add3_u32 v33, v33, v34, s18
	ds_write_b16_d16_hi v22, v33 offset:19040
	v_and_b32_e32 v33, 0xffff0000, v17
	v_mul_f32_e32 v33, v32, v33
	v_bfe_u32 v34, v33, 16, 1
	v_add3_u32 v33, v33, v34, s18
	ds_write_b16_d16_hi v22, v33 offset:19312
	v_lshlrev_b32_e32 v33, 16, v10
	v_mul_f32_e32 v33, v32, v33
	v_bfe_u32 v34, v33, 16, 1
	v_add3_u32 v33, v33, v34, s18
	ds_write_b16_d16_hi v22, v33 offset:19584
	v_and_b32_e32 v33, 0xffff0000, v10
	v_mul_f32_e32 v33, v32, v33
	v_bfe_u32 v34, v33, 16, 1
	v_add3_u32 v33, v33, v34, s18
	ds_write_b16_d16_hi v22, v33 offset:19856
	v_lshlrev_b32_e32 v33, 16, v11
	v_mul_f32_e32 v33, v32, v33
	v_bfe_u32 v34, v33, 16, 1
	v_add3_u32 v33, v33, v34, s18
	ds_write_b16_d16_hi v22, v33 offset:20128
	v_and_b32_e32 v33, 0xffff0000, v11
	v_mul_f32_e32 v33, v32, v33
	v_bfe_u32 v34, v33, 16, 1
	v_add3_u32 v33, v33, v34, s18
	ds_write_b16_d16_hi v22, v33 offset:20400
	v_lshlrev_b32_e32 v33, 16, v12
	v_mul_f32_e32 v33, v32, v33
	v_bfe_u32 v34, v33, 16, 1
	v_add3_u32 v33, v33, v34, s18
	ds_write_b16_d16_hi v22, v33 offset:20672
	v_and_b32_e32 v33, 0xffff0000, v12
	v_mul_f32_e32 v33, v32, v33
	v_bfe_u32 v34, v33, 16, 1
	v_add3_u32 v33, v33, v34, s18
	ds_write_b16_d16_hi v22, v33 offset:20944
	v_lshlrev_b32_e32 v33, 16, v13
	v_mul_f32_e32 v33, v32, v33
	v_bfe_u32 v34, v33, 16, 1
	v_add3_u32 v33, v33, v34, s18
	ds_write_b16_d16_hi v22, v33 offset:21216
	v_and_b32_e32 v33, 0xffff0000, v13
	v_mul_f32_e32 v32, v32, v33
	v_bfe_u32 v33, v32, 16, 1
	v_add3_u32 v32, v32, v33, s18
	ds_write_b16_d16_hi v22, v32 offset:21488
	s_waitcnt lgkmcnt(0)
	s_barrier
	s_cbranch_vccnz .LBB0_289
	s_and_b32 s6, s12, 0xfffff000
	s_and_b32 s20, s2, 0xf80
	s_or_b32 s6, s6, s20
	v_add_u32_e32 v2, s6, v1
	v_ashrrev_i32_e32 v3, 31, v2
	v_lshlrev_b64 v[2:3], 12, v[2:3]
	s_and_b32 s6, s0, 0x1c0
	v_lshl_add_u64 v[2:3], s[4:5], 0, v[2:3]
	s_lshl_b32 s6, s6, 1
	v_lshl_add_u64 v[2:3], v[2:3], 0, s[6:7]
	v_lshl_add_u64 v[32:33], v[2:3], 0, v[18:19]
	global_load_dwordx4 v[2:5], v[32:33], off offset:2048
	global_load_dwordx4 v[6:9], v[32:33], off offset:2064
	global_load_dwordx4 v[10:13], v[32:33], off offset:1040
	global_load_dwordx4 v[14:17], v[32:33], off offset:1024
	s_branch .LBB0_289
.LBB0_292:
	s_mov_b32 s96, s99
	s_mov_b32 s82, s100
	s_cmp_lt_i32 s81, 4
	s_waitcnt vmcnt(0) lgkmcnt(0)
	s_barrier
	s_cbranch_scc1 .LBB0_346
	s_waitcnt vmcnt(0)
	s_barrier
	s_mov_b64 s[4:5], exec
	v_readlane_b32 s0, v254, 1
	v_readlane_b32 s1, v254, 2
	s_and_b64 s[0:1], s[4:5], s[0:1]
	s_mov_b64 exec, s[0:1]
	s_cbranch_execz .LBB0_345
	s_add_i32 s0, 0, 0x20000
	v_mov_b32_e32 v1, s0
	s_waitcnt vmcnt(0) expcnt(0) lgkmcnt(0)
	ds_read_b32 v3, v1
	s_add_i32 s0, 0, 0x20004
	v_mov_b32_e32 v1, s0
	ds_read_b32 v1, v1
	s_waitcnt lgkmcnt(1)
	v_cmp_ne_u32_e32 vcc, 0, v3
	s_cbranch_vccnz .LBB0_309
	s_add_u32 s6, s78, 0x4200
	s_addc_u32 s7, s79, 0
	s_add_u32 s8, s78, 0x4400
	s_addc_u32 s9, s79, 0
	s_add_u32 s10, s78, 0x4500
	s_addc_u32 s11, s79, 0
	s_add_u32 s12, s78, 0x4600
	s_addc_u32 s13, s79, 0
	s_add_u32 s14, s78, 0x4700
	s_addc_u32 s15, s79, 0
	s_add_u32 s16, s78, 0x4800
	s_addc_u32 s17, s79, 0
	s_add_u32 s18, s78, 0x4900
	s_addc_u32 s19, s79, 0
	s_add_u32 s20, s78, 0x4a00
	s_addc_u32 s21, s79, 0
	s_add_u32 s22, s78, 0x4b00
	s_addc_u32 s23, s79, 0
	s_add_u32 s24, s78, 0x4c00
	s_addc_u32 s25, s79, 0
	s_add_u32 s26, s78, 0x4d00
	s_addc_u32 s27, s79, 0
	s_add_u32 s28, s78, 0x4e00
	s_addc_u32 s29, s79, 0
	s_add_u32 s30, s78, 0x4f00
	s_addc_u32 s31, s79, 0
	s_add_u32 s34, s78, 0x5000
	s_addc_u32 s35, s79, 0
	s_add_u32 s36, s78, 0x5100
	s_addc_u32 s37, s79, 0
	s_add_u32 s38, s78, 0x5200
	v_readlane_b32 s0, v254, 0
	s_addc_u32 s39, s79, 0
	s_mul_i32 s0, s83, s0
	s_add_u32 s40, s78, 0x5300
	s_mul_i32 s0, s0, s82
	s_addc_u32 s41, s79, 0
	s_mov_b32 s1, 1
	v_mov_b32_e32 v17, 0
	s_branch .LBB0_297

; template <class Epi, class Sched, bool ALIGN_EPI = false, bool SP2 = false>
; __device__ __forceinline__ void gemm_phase(PG8_LAS unsigned char* lds, const Gemm g, const Sched& S, const Epi& E) {
;     ...
; #pragma unroll
;         for (int a = 0; a < 2; ++a)
; #pragma unroll
;             for (int b = 0; b < 2; ++b)
; #pragma unroll
;                 for (int m = 0; m < 4; ++m)
; #pragma unroll
;                     for (int n = 0; n < 2; ++n) acc[a][b][m][n] = (f32x4){0.f, 0.f, 0.f, 0.f};
.LBB0_429:
	s_add_u32 s2, s42, 0x100
	v_mov_b64_e32 v[2:3], 0
	v_mov_b64_e32 v[4:5], 0
	v_mov_b64_e32 v[6:7], 0
	v_mov_b64_e32 v[8:9], 0
	v_mov_b64_e32 v[10:11], 0
	v_mov_b64_e32 v[12:13], 0
	v_mov_b64_e32 v[14:15], 0
	v_mov_b64_e32 v[16:17], 0
	v_mov_b64_e32 v[18:19], 0
	v_mov_b64_e32 v[20:21], 0
	v_mov_b64_e32 v[22:23], 0
	v_mov_b64_e32 v[24:25], 0
	v_mov_b64_e32 v[26:27], 0
	v_mov_b64_e32 v[28:29], 0
	v_mov_b64_e32 v[30:31], 0
	v_mov_b64_e32 v[32:33], 0
	v_mov_b64_e32 v[34:35], 0
	v_mov_b64_e32 v[36:37], 0
	v_mov_b64_e32 v[38:39], 0
	v_mov_b64_e32 v[40:41], 0
	v_mov_b64_e32 v[42:43], 0
	v_mov_b64_e32 v[44:45], 0
	v_mov_b64_e32 v[46:47], 0
	v_mov_b64_e32 v[48:49], 0
	v_mov_b64_e32 v[50:51], 0
	v_mov_b64_e32 v[52:53], 0
	v_mov_b64_e32 v[54:55], 0
	v_mov_b64_e32 v[56:57], 0
	v_mov_b64_e32 v[58:59], 0
	v_mov_b64_e32 v[60:61], 0
	v_mov_b64_e32 v[70:71], 0
	v_mov_b64_e32 v[72:73], 0
	v_mov_b64_e32 v[74:75], 0
	v_mov_b64_e32 v[76:77], 0
	v_mov_b64_e32 v[78:79], 0
	v_mov_b64_e32 v[80:81], 0
	v_mov_b64_e32 v[82:83], 0
	v_mov_b64_e32 v[84:85], 0
	v_mov_b64_e32 v[86:87], 0
	v_mov_b64_e32 v[88:89], 0
	v_mov_b64_e32 v[90:91], 0
	v_mov_b64_e32 v[92:93], 0
	v_mov_b64_e32 v[94:95], 0
	v_mov_b64_e32 v[96:97], 0
	v_mov_b64_e32 v[98:99], 0
	v_mov_b64_e32 v[100:101], 0
	v_mov_b64_e32 v[102:103], 0
	v_mov_b64_e32 v[104:105], 0
	v_mov_b64_e32 v[106:107], 0
	v_mov_b64_e32 v[108:109], 0
	v_mov_b64_e32 v[110:111], 0
	v_mov_b64_e32 v[112:113], 0
	v_mov_b64_e32 v[114:115], 0
	v_mov_b64_e32 v[116:117], 0
	v_mov_b64_e32 v[118:119], 0
	v_mov_b64_e32 v[120:121], 0
	v_mov_b64_e32 v[122:123], 0
	v_mov_b64_e32 v[124:125], 0
	v_mov_b64_e32 v[126:127], 0
	v_mov_b64_e32 v[128:129], 0
	v_mov_b64_e32 v[130:131], 0
	v_mov_b64_e32 v[132:133], 0
	v_mov_b64_e32 v[134:135], 0
	v_mov_b64_e32 v[136:137], 0
	s_addc_u32 s5, s43, 0
	s_mov_b32 s33, -2

;     __device__ __forceinline__ bool next(int i, Unit& u) const { const int L = i * G + c; if (L >= nM * nN * ng) return false; const int per = nM * nN, r = L % per; u.g = L / per; u.pn = r / nM; u.pm = r % nM; return true; }
; template <class Epi, class Sched, bool ALIGN_EPI = false, bool SP2 = false>
; __device__ __forceinline__ void gemm_phase(PG8_LAS unsigned char* lds, const Gemm g, const Sched& S, const Epi& E) {
;     ...
;         const bool has_next = S.next(ui + 1, nxt);
;         const char* nA = has_next ? (const char*)g.A + (size_t)nxt.g * g.gsA * 2 + (size_t)nxt.pm * tstepA : cA; const char* nB = has_next ? (const char*)g.Bt + (size_t)nxt.g * g.gsB * 2 + (size_t)nxt.pn * tstepB : cB;
;         for (int t = 0; t < nt; t += 2) {
;             const bool last = (t == nt - 2);
;             const char* a1 = cA + (size_t)(t + 1) * kstep;
;             const char* a2 = last ? nA : cA + (size_t)(t + 2) * kstep; const char* b2 = last ? nB : cB + (size_t)(t + 2) * kstep;
;             const char* a3 = a2 + kstep; const char* b3 = b2 + kstep;
;     ...
; #pragma unroll
;         for (int a = 0; a < 2; ++a)
; #pragma unroll
;             for (int b = 0; b < 2; ++b)
; #pragma unroll
;                 for (int m = 0; m < 4; ++m)
; #pragma unroll
;                     for (int n = 0; n < 2; ++n) acc[a][b][m][n] = (f32x4){0.f, 0.f, 0.f, 0.f};
.LBB0_522:
	s_ashr_i32 s19, s18, 31
	s_lshl_b64 s[20:21], s[18:19], 18
	s_add_u32 s20, s8, s20
	s_addc_u32 s21, s9, s21
	s_and_b64 s[22:23], s[6:7], exec
	s_cselect_b32 s19, s21, s27
	s_cselect_b32 s44, s20, s26
	s_ashr_i32 s17, s16, 31
	s_lshl_b64 s[22:23], s[16:17], 18
	s_add_u32 s22, s33, s22
	s_addc_u32 s23, s34, s23
	s_and_b64 s[30:31], s[6:7], exec
	s_cselect_b32 s17, s23, s29
	s_cselect_b32 s45, s22, s28
	s_add_u32 s26, s26, 0x20080
	s_addc_u32 s27, s27, 0
	s_add_u32 s46, s28, 0x100
	v_mov_b64_e32 v[2:3], 0
	v_mov_b64_e32 v[4:5], 0
	v_mov_b64_e32 v[6:7], 0
	v_mov_b64_e32 v[8:9], 0
	v_mov_b64_e32 v[10:11], 0
	v_mov_b64_e32 v[12:13], 0
	v_mov_b64_e32 v[14:15], 0
	v_mov_b64_e32 v[16:17], 0
	v_mov_b64_e32 v[18:19], 0
	v_mov_b64_e32 v[20:21], 0
	v_mov_b64_e32 v[22:23], 0
	v_mov_b64_e32 v[24:25], 0
	v_mov_b64_e32 v[26:27], 0
	v_mov_b64_e32 v[28:29], 0
	v_mov_b64_e32 v[30:31], 0
	v_mov_b64_e32 v[32:33], 0
	v_mov_b64_e32 v[34:35], 0
	v_mov_b64_e32 v[36:37], 0
	v_mov_b64_e32 v[38:39], 0
	v_mov_b64_e32 v[40:41], 0
	v_mov_b64_e32 v[42:43], 0
	v_mov_b64_e32 v[44:45], 0
	v_mov_b64_e32 v[46:47], 0
	v_mov_b64_e32 v[48:49], 0
	v_mov_b64_e32 v[50:51], 0
	v_mov_b64_e32 v[52:53], 0
	v_mov_b64_e32 v[54:55], 0
	v_mov_b64_e32 v[56:57], 0
	v_mov_b64_e32 v[58:59], 0
	v_mov_b64_e32 v[60:61], 0
	v_mov_b64_e32 v[62:63], 0
	v_mov_b64_e32 v[64:65], 0
	v_mov_b64_e32 v[66:67], 0
	v_mov_b64_e32 v[68:69], 0
	v_mov_b64_e32 v[70:71], 0
	v_mov_b64_e32 v[72:73], 0
	v_mov_b64_e32 v[74:75], 0
	v_mov_b64_e32 v[76:77], 0
	v_mov_b64_e32 v[78:79], 0
	v_mov_b64_e32 v[80:81], 0
	v_mov_b64_e32 v[82:83], 0
	v_mov_b64_e32 v[84:85], 0
	v_mov_b64_e32 v[86:87], 0
	v_mov_b64_e32 v[88:89], 0
	v_mov_b64_e32 v[90:91], 0
	v_mov_b64_e32 v[92:93], 0
	v_mov_b64_e32 v[94:95], 0
	v_mov_b64_e32 v[96:97], 0
	v_mov_b64_e32 v[98:99], 0
	v_mov_b64_e32 v[100:101], 0
	v_mov_b64_e32 v[102:103], 0
	v_mov_b64_e32 v[104:105], 0
	v_mov_b64_e32 v[106:107], 0
	v_mov_b64_e32 v[108:109], 0
	v_mov_b64_e32 v[110:111], 0
	v_mov_b64_e32 v[112:113], 0
	v_mov_b64_e32 v[114:115], 0
	v_mov_b64_e32 v[116:117], 0
	v_mov_b64_e32 v[118:119], 0
	v_mov_b64_e32 v[120:121], 0
	v_mov_b64_e32 v[122:123], 0
	v_mov_b64_e32 v[124:125], 0
	v_mov_b64_e32 v[126:127], 0
	v_mov_b64_e32 v[128:129], 0
	s_addc_u32 s47, s29, 0
	s_mov_b32 s48, -2
	s_waitcnt lgkmcnt(0)

;     __device__ __forceinline__ bool next(int i, Unit& u) const { const int L = i * G + c; if (L >= nM * nN * ng) return false; const int per = nM * nN, r = L % per; u.g = L / per; u.pn = r / nM; u.pm = r % nM; return true; }
; template <class Epi, class Sched, bool ALIGN_EPI = false, bool SP2 = false>
; __device__ __forceinline__ void gemm_phase(PG8_LAS unsigned char* lds, const Gemm g, const Sched& S, const Epi& E) {
;     ...
;         const bool has_next = S.next(ui + 1, nxt);
;         const char* nA = has_next ? (const char*)g.A + (size_t)nxt.g * g.gsA * 2 + (size_t)nxt.pm * tstepA : cA; const char* nB = has_next ? (const char*)g.Bt + (size_t)nxt.g * g.gsB * 2 + (size_t)nxt.pn * tstepB : cB;
;         for (int t = 0; t < nt; t += 2) {
;             const bool last = (t == nt - 2);
;             const char* a1 = cA + (size_t)(t + 1) * kstep;
;             const char* a2 = last ? nA : cA + (size_t)(t + 2) * kstep; const char* b2 = last ? nB : cB + (size_t)(t + 2) * kstep;
;             const char* a3 = a2 + kstep; const char* b3 = b2 + kstep;
;     ...
; #pragma unroll
;         for (int a = 0; a < 2; ++a)
; #pragma unroll
;             for (int b = 0; b < 2; ++b)
; #pragma unroll
;                 for (int m = 0; m < 4; ++m)
; #pragma unroll
;                     for (int n = 0; n < 2; ++n) acc[a][b][m][n] = (f32x4){0.f, 0.f, 0.f, 0.f};
.LBB0_604:
	s_ashr_i32 s25, s24, 31
	s_lshl_b64 s[26:27], s[24:25], 19
	s_add_u32 s26, s0, s26
	s_addc_u32 s27, s1, s27
	s_and_b64 s[28:29], s[8:9], exec
	s_cselect_b32 s25, s27, s35
	s_cselect_b32 s31, s26, s34
	s_ashr_i32 s23, s22, 31
	s_lshl_b64 s[28:29], s[22:23], 19
	s_add_u32 s28, s2, s28
	s_addc_u32 s29, s3, s29
	s_and_b64 s[38:39], s[8:9], exec
	s_cselect_b32 s23, s29, s37
	s_cselect_b32 s53, s28, s36
	s_add_u32 s34, s34, 0x40080
	s_addc_u32 s35, s35, 0
	s_add_u32 s54, s36, 0x100
	v_mov_b64_e32 v[2:3], 0
	v_mov_b64_e32 v[4:5], 0
	v_mov_b64_e32 v[6:7], 0
	v_mov_b64_e32 v[8:9], 0
	v_mov_b64_e32 v[10:11], 0
	v_mov_b64_e32 v[12:13], 0
	v_mov_b64_e32 v[14:15], 0
	v_mov_b64_e32 v[16:17], 0
	v_mov_b64_e32 v[18:19], 0
	v_mov_b64_e32 v[20:21], 0
	v_mov_b64_e32 v[22:23], 0
	v_mov_b64_e32 v[24:25], 0
	v_mov_b64_e32 v[26:27], 0
	v_mov_b64_e32 v[28:29], 0
	v_mov_b64_e32 v[30:31], 0
	v_mov_b64_e32 v[32:33], 0
	v_mov_b64_e32 v[34:35], 0
	v_mov_b64_e32 v[36:37], 0
	v_mov_b64_e32 v[38:39], 0
	v_mov_b64_e32 v[40:41], 0
	v_mov_b64_e32 v[42:43], 0
	v_mov_b64_e32 v[44:45], 0
	v_mov_b64_e32 v[46:47], 0
	v_mov_b64_e32 v[48:49], 0
	v_mov_b64_e32 v[50:51], 0
	v_mov_b64_e32 v[52:53], 0
	v_mov_b64_e32 v[54:55], 0
	v_mov_b64_e32 v[56:57], 0
	v_mov_b64_e32 v[58:59], 0
	v_mov_b64_e32 v[60:61], 0
	v_mov_b64_e32 v[62:63], 0
	v_mov_b64_e32 v[64:65], 0
	v_mov_b64_e32 v[66:67], 0
	v_mov_b64_e32 v[68:69], 0
	v_mov_b64_e32 v[70:71], 0
	v_mov_b64_e32 v[72:73], 0
	v_mov_b64_e32 v[74:75], 0
	v_mov_b64_e32 v[76:77], 0
	v_mov_b64_e32 v[78:79], 0
	v_mov_b64_e32 v[80:81], 0
	v_mov_b64_e32 v[82:83], 0
	v_mov_b64_e32 v[84:85], 0
	v_mov_b64_e32 v[86:87], 0
	v_mov_b64_e32 v[88:89], 0
	v_mov_b64_e32 v[90:91], 0
	v_mov_b64_e32 v[92:93], 0
	v_mov_b64_e32 v[94:95], 0
	v_mov_b64_e32 v[96:97], 0
	v_mov_b64_e32 v[98:99], 0
	v_mov_b64_e32 v[100:101], 0
	v_mov_b64_e32 v[102:103], 0
	v_mov_b64_e32 v[104:105], 0
	v_mov_b64_e32 v[106:107], 0
	v_mov_b64_e32 v[108:109], 0
	v_mov_b64_e32 v[110:111], 0
	v_mov_b64_e32 v[112:113], 0
	v_mov_b64_e32 v[114:115], 0
	v_mov_b64_e32 v[116:117], 0
	v_mov_b64_e32 v[118:119], 0
	v_mov_b64_e32 v[120:121], 0
	v_mov_b64_e32 v[122:123], 0
	v_mov_b64_e32 v[124:125], 0
	v_mov_b64_e32 v[126:127], 0
	v_mov_b64_e32 v[128:129], 0
	s_addc_u32 s55, s37, 0
	s_mov_b32 s56, -2
	s_waitcnt lgkmcnt(0)
	s_waitcnt lgkmcnt(0)

;     __device__ __forceinline__ bool next(int i, Unit& u) const { const int L = i * G + c; if (L >= nM * nN * ng) return false; const int per = nM * nN, r = L % per; u.g = L / per; u.pn = r / nM; u.pm = r % nM; return true; }
; template <class Epi, class Sched, bool ALIGN_EPI = false, bool SP2 = false>
; __device__ __forceinline__ void gemm_phase(PG8_LAS unsigned char* lds, const Gemm g, const Sched& S, const Epi& E) {
;     ...
;         const bool has_next = S.next(ui + 1, nxt);
;         const char* nA = has_next ? (const char*)g.A + (size_t)nxt.g * g.gsA * 2 + (size_t)nxt.pm * tstepA : cA; const char* nB = has_next ? (const char*)g.Bt + (size_t)nxt.g * g.gsB * 2 + (size_t)nxt.pn * tstepB : cB;
;         for (int t = 0; t < nt; t += 2) {
;             const bool last = (t == nt - 2);
;             const char* a1 = cA + (size_t)(t + 1) * kstep;
;             const char* a2 = last ? nA : cA + (size_t)(t + 2) * kstep; const char* b2 = last ? nB : cB + (size_t)(t + 2) * kstep;
;             const char* a3 = a2 + kstep; const char* b3 = b2 + kstep;
;     ...
; #pragma unroll
;         for (int a = 0; a < 2; ++a)
; #pragma unroll
;             for (int b = 0; b < 2; ++b)
; #pragma unroll
;                 for (int m = 0; m < 4; ++m)
; #pragma unroll
;                     for (int n = 0; n < 2; ++n) acc[a][b][m][n] = (f32x4){0.f, 0.f, 0.f, 0.f};
.LBB0_690:
	s_ashr_i32 s17, s16, 31
	s_lshl_b64 s[18:19], s[16:17], 19
	s_add_u32 s18, s0, s18
	s_addc_u32 s19, s1, s19
	s_and_b64 s[20:21], s[6:7], exec
	s_cselect_b32 s17, s19, s25
	s_cselect_b32 s46, s18, s24
	s_ashr_i32 s15, s14, 31
	s_lshl_b64 s[20:21], s[14:15], 19
	s_add_u32 s20, s2, s20
	s_addc_u32 s21, s3, s21
	s_and_b64 s[28:29], s[6:7], exec
	s_cselect_b32 s15, s21, s27
	s_cselect_b32 s47, s20, s26
	s_add_u32 s24, s24, 0x40080
	s_addc_u32 s25, s25, 0
	s_add_u32 s48, s26, 0x100
	v_mov_b64_e32 v[2:3], 0
	v_mov_b64_e32 v[4:5], 0
	v_mov_b64_e32 v[6:7], 0
	v_mov_b64_e32 v[8:9], 0
	v_mov_b64_e32 v[10:11], 0
	v_mov_b64_e32 v[12:13], 0
	v_mov_b64_e32 v[14:15], 0
	v_mov_b64_e32 v[16:17], 0
	v_mov_b64_e32 v[18:19], 0
	v_mov_b64_e32 v[20:21], 0
	v_mov_b64_e32 v[22:23], 0
	v_mov_b64_e32 v[24:25], 0
	v_mov_b64_e32 v[26:27], 0
	v_mov_b64_e32 v[28:29], 0
	v_mov_b64_e32 v[30:31], 0
	v_mov_b64_e32 v[32:33], 0
	v_mov_b64_e32 v[34:35], 0
	v_mov_b64_e32 v[36:37], 0
	v_mov_b64_e32 v[38:39], 0
	v_mov_b64_e32 v[40:41], 0
	v_mov_b64_e32 v[42:43], 0
	v_mov_b64_e32 v[44:45], 0
	v_mov_b64_e32 v[46:47], 0
	v_mov_b64_e32 v[48:49], 0
	v_mov_b64_e32 v[50:51], 0
	v_mov_b64_e32 v[52:53], 0
	v_mov_b64_e32 v[54:55], 0
	v_mov_b64_e32 v[56:57], 0
	v_mov_b64_e32 v[58:59], 0
	v_mov_b64_e32 v[60:61], 0
	v_mov_b64_e32 v[62:63], 0
	v_mov_b64_e32 v[64:65], 0
	v_mov_b64_e32 v[66:67], 0
	v_mov_b64_e32 v[68:69], 0
	v_mov_b64_e32 v[70:71], 0
	v_mov_b64_e32 v[72:73], 0
	v_mov_b64_e32 v[74:75], 0
	v_mov_b64_e32 v[76:77], 0
	v_mov_b64_e32 v[78:79], 0
	v_mov_b64_e32 v[80:81], 0
	v_mov_b64_e32 v[82:83], 0
	v_mov_b64_e32 v[84:85], 0
	v_mov_b64_e32 v[86:87], 0
	v_mov_b64_e32 v[88:89], 0
	v_mov_b64_e32 v[90:91], 0
	v_mov_b64_e32 v[92:93], 0
	v_mov_b64_e32 v[94:95], 0
	v_mov_b64_e32 v[96:97], 0
	v_mov_b64_e32 v[98:99], 0
	v_mov_b64_e32 v[100:101], 0
	v_mov_b64_e32 v[102:103], 0
	v_mov_b64_e32 v[104:105], 0
	v_mov_b64_e32 v[106:107], 0
	v_mov_b64_e32 v[108:109], 0
	v_mov_b64_e32 v[110:111], 0
	v_mov_b64_e32 v[112:113], 0
	v_mov_b64_e32 v[114:115], 0
	v_mov_b64_e32 v[116:117], 0
	v_mov_b64_e32 v[118:119], 0
	v_mov_b64_e32 v[120:121], 0
	v_mov_b64_e32 v[122:123], 0
	v_mov_b64_e32 v[124:125], 0
	v_mov_b64_e32 v[126:127], 0
	v_mov_b64_e32 v[128:129], 0
	s_addc_u32 s49, s27, 0
	s_mov_b32 s50, -2

; template <class Epi, class Sched, bool ALIGN_EPI = false, bool SP2 = false>
; __device__ __forceinline__ void gemm_phase(PG8_LAS unsigned char* lds, const Gemm g, const Sched& S, const Epi& E) {
;     ...
; #pragma unroll
;         for (int a = 0; a < 2; ++a)
; #pragma unroll
;             for (int b = 0; b < 2; ++b)
; #pragma unroll
;                 for (int m = 0; m < 4; ++m)
; #pragma unroll
;                     for (int n = 0; n < 2; ++n) acc[a][b][m][n] = (f32x4){0.f, 0.f, 0.f, 0.f};
.LBB0_775:
	s_add_u32 s4, s28, 0x100
	v_mov_b64_e32 v[2:3], 0
	v_mov_b64_e32 v[4:5], 0
	v_mov_b64_e32 v[6:7], 0
	v_mov_b64_e32 v[8:9], 0
	v_mov_b64_e32 v[10:11], 0
	v_mov_b64_e32 v[12:13], 0
	v_mov_b64_e32 v[14:15], 0
	v_mov_b64_e32 v[16:17], 0
	v_mov_b64_e32 v[18:19], 0
	v_mov_b64_e32 v[20:21], 0
	v_mov_b64_e32 v[22:23], 0
	v_mov_b64_e32 v[24:25], 0
	v_mov_b64_e32 v[26:27], 0
	v_mov_b64_e32 v[28:29], 0
	v_mov_b64_e32 v[30:31], 0
	v_mov_b64_e32 v[32:33], 0
	v_mov_b64_e32 v[34:35], 0
	v_mov_b64_e32 v[36:37], 0
	v_mov_b64_e32 v[38:39], 0
	v_mov_b64_e32 v[40:41], 0
	v_mov_b64_e32 v[42:43], 0
	v_mov_b64_e32 v[44:45], 0
	v_mov_b64_e32 v[46:47], 0
	v_mov_b64_e32 v[48:49], 0
	v_mov_b64_e32 v[50:51], 0
	v_mov_b64_e32 v[52:53], 0
	v_mov_b64_e32 v[54:55], 0
	v_mov_b64_e32 v[56:57], 0
	v_mov_b64_e32 v[58:59], 0
	v_mov_b64_e32 v[60:61], 0
	v_mov_b64_e32 v[62:63], 0
	v_mov_b64_e32 v[64:65], 0
	v_mov_b64_e32 v[66:67], 0
	v_mov_b64_e32 v[68:69], 0
	v_mov_b64_e32 v[70:71], 0
	v_mov_b64_e32 v[72:73], 0
	v_mov_b64_e32 v[74:75], 0
	v_mov_b64_e32 v[76:77], 0
	v_mov_b64_e32 v[78:79], 0
	v_mov_b64_e32 v[80:81], 0
	v_mov_b64_e32 v[82:83], 0
	v_mov_b64_e32 v[84:85], 0
	v_mov_b64_e32 v[86:87], 0
	v_mov_b64_e32 v[88:89], 0
	v_mov_b64_e32 v[90:91], 0
	v_mov_b64_e32 v[92:93], 0
	v_mov_b64_e32 v[94:95], 0
	v_mov_b64_e32 v[96:97], 0
	v_mov_b64_e32 v[98:99], 0
	v_mov_b64_e32 v[100:101], 0
	v_mov_b64_e32 v[102:103], 0
	v_mov_b64_e32 v[104:105], 0
	v_mov_b64_e32 v[106:107], 0
	v_mov_b64_e32 v[108:109], 0
	v_mov_b64_e32 v[110:111], 0
	v_mov_b64_e32 v[112:113], 0
	v_mov_b64_e32 v[114:115], 0
	v_mov_b64_e32 v[116:117], 0
	v_mov_b64_e32 v[118:119], 0
	v_mov_b64_e32 v[120:121], 0
	v_mov_b64_e32 v[122:123], 0
	v_mov_b64_e32 v[124:125], 0
	v_mov_b64_e32 v[126:127], 0
	v_mov_b64_e32 v[128:129], 0
	s_addc_u32 s53, s29, 0
	s_mov_b32 s54, -2
	s_waitcnt lgkmcnt(0)

; template <class Epi, class Sched, bool ALIGN_EPI = false, bool SP2 = false>
; __device__ __forceinline__ void gemm_phase(PG8_LAS unsigned char* lds, const Gemm g, const Sched& S, const Epi& E) {
;     ...
;     f32x4 acc[2][2][4][2];
; #pragma unroll
;     for (int a = 0; a < 2; ++a)
; #pragma unroll
;         for (int b = 0; b < 2; ++b)
; #pragma unroll
;             for (int m = 0; m < 4; ++m)
; #pragma unroll
;                 for (int n = 0; n < 2; ++n) acc[a][b][m][n] = (f32x4){0.f, 0.f, 0.f, 0.f};
;     ...
; #pragma unroll
;         for (int a = 0; a < 2; ++a)
; #pragma unroll
;             for (int b = 0; b < 2; ++b)
; #pragma unroll
;                 for (int m = 0; m < 4; ++m)
; #pragma unroll
;                     for (int n = 0; n < 2; ++n) acc[a][b][m][n] = (f32x4){0.f, 0.f, 0.f, 0.f};
.LBB0_819:
	v_mov_b32_e32 v125, 0
	s_andn2_b64 vcc, exec, s[22:23]
	v_mov_b32_e32 v124, v125
	v_mov_b32_e32 v123, v125
	v_mov_b32_e32 v122, v125
	v_mov_b32_e32 v129, v125
	v_mov_b32_e32 v128, v125
	v_mov_b32_e32 v127, v125
	v_mov_b32_e32 v126, v125
	v_mov_b32_e32 v113, v125
	v_mov_b32_e32 v112, v125
	v_mov_b32_e32 v111, v125
	v_mov_b32_e32 v110, v125
	v_mov_b32_e32 v109, v125
	v_mov_b32_e32 v108, v125
	v_mov_b32_e32 v107, v125
	v_mov_b32_e32 v106, v125
	v_mov_b32_e32 v97, v125
	v_mov_b32_e32 v96, v125
	v_mov_b32_e32 v95, v125
	v_mov_b32_e32 v94, v125
	v_mov_b32_e32 v93, v125
	v_mov_b32_e32 v92, v125
	v_mov_b32_e32 v91, v125
	v_mov_b32_e32 v90, v125
	v_mov_b32_e32 v81, v125
	v_mov_b32_e32 v80, v125
	v_mov_b32_e32 v79, v125
	v_mov_b32_e32 v78, v125
	v_mov_b32_e32 v77, v125
	v_mov_b32_e32 v76, v125
	v_mov_b32_e32 v75, v125
	v_mov_b32_e32 v74, v125
	v_mov_b32_e32 v121, v125
	v_mov_b32_e32 v120, v125
	v_mov_b32_e32 v119, v125
	v_mov_b32_e32 v118, v125
	v_mov_b32_e32 v117, v125
	v_mov_b32_e32 v116, v125
	v_mov_b32_e32 v115, v125
	v_mov_b32_e32 v114, v125
	v_mov_b32_e32 v105, v125
	v_mov_b32_e32 v104, v125
	v_mov_b32_e32 v103, v125
	v_mov_b32_e32 v102, v125
	v_mov_b32_e32 v101, v125
	v_mov_b32_e32 v100, v125
	v_mov_b32_e32 v99, v125
	v_mov_b32_e32 v98, v125
	v_mov_b32_e32 v89, v125
	v_mov_b32_e32 v88, v125
	v_mov_b32_e32 v87, v125
	v_mov_b32_e32 v86, v125
	v_mov_b32_e32 v85, v125
	v_mov_b32_e32 v84, v125
	v_mov_b32_e32 v83, v125
	v_mov_b32_e32 v82, v125
	v_mov_b32_e32 v73, v125
	v_mov_b32_e32 v72, v125
	v_mov_b32_e32 v71, v125
	v_mov_b32_e32 v70, v125
	v_mov_b32_e32 v69, v125
	v_mov_b32_e32 v68, v125
	v_mov_b32_e32 v67, v125
	v_mov_b32_e32 v66, v125
	v_mov_b32_e32 v65, v125
	v_mov_b32_e32 v64, v125
	v_mov_b32_e32 v63, v125
	v_mov_b32_e32 v62, v125
	v_mov_b32_e32 v61, v125
	v_mov_b32_e32 v60, v125
	v_mov_b32_e32 v59, v125
	v_mov_b32_e32 v58, v125
	v_mov_b32_e32 v49, v125
	v_mov_b32_e32 v48, v125
	v_mov_b32_e32 v47, v125
	v_mov_b32_e32 v46, v125
	v_mov_b32_e32 v45, v125
	v_mov_b32_e32 v44, v125
	v_mov_b32_e32 v43, v125
	v_mov_b32_e32 v42, v125
	v_mov_b32_e32 v33, v125
	v_mov_b32_e32 v32, v125
	v_mov_b32_e32 v31, v125
	v_mov_b32_e32 v30, v125
	v_mov_b32_e32 v29, v125
	v_mov_b32_e32 v28, v125
	v_mov_b32_e32 v27, v125
	v_mov_b32_e32 v26, v125
	v_mov_b32_e32 v17, v125
	v_mov_b32_e32 v16, v125
	v_mov_b32_e32 v15, v125
	v_mov_b32_e32 v14, v125
	v_mov_b32_e32 v13, v125
	v_mov_b32_e32 v12, v125
	v_mov_b32_e32 v11, v125
	v_mov_b32_e32 v10, v125
	v_mov_b32_e32 v57, v125
	v_mov_b32_e32 v56, v125
	v_mov_b32_e32 v55, v125
	v_mov_b32_e32 v54, v125
	v_mov_b32_e32 v53, v125
	v_mov_b32_e32 v52, v125
	v_mov_b32_e32 v51, v125
	v_mov_b32_e32 v50, v125
	v_mov_b32_e32 v41, v125
	v_mov_b32_e32 v40, v125
	v_mov_b32_e32 v39, v125
	v_mov_b32_e32 v38, v125
	v_mov_b32_e32 v37, v125
	v_mov_b32_e32 v36, v125
	v_mov_b32_e32 v35, v125
	v_mov_b32_e32 v34, v125
	v_mov_b32_e32 v25, v125
	v_mov_b32_e32 v24, v125
	v_mov_b32_e32 v23, v125
	v_mov_b32_e32 v22, v125
	v_mov_b32_e32 v21, v125
	v_mov_b32_e32 v20, v125
	v_mov_b32_e32 v19, v125
	v_mov_b32_e32 v18, v125
	v_mov_b32_e32 v9, v125
	v_mov_b32_e32 v8, v125
	v_mov_b32_e32 v7, v125
	v_mov_b32_e32 v6, v125
	v_mov_b32_e32 v5, v125
	v_mov_b32_e32 v4, v125
	v_mov_b32_e32 v3, v125
	v_mov_b32_e32 v2, v125
	s_cbranch_vccnz .LBB0_822
	s_add_u32 s38, s38, 0x80
	s_addc_u32 s39, s39, 0
	s_add_u32 s63, s40, 0x100
	v_mov_b64_e32 v[2:3], 0
	v_mov_b64_e32 v[4:5], 0
	v_mov_b64_e32 v[6:7], 0
	v_mov_b64_e32 v[8:9], 0
	v_mov_b64_e32 v[10:11], 0
	v_mov_b64_e32 v[12:13], 0
	v_mov_b64_e32 v[14:15], 0
	v_mov_b64_e32 v[16:17], 0
	v_mov_b64_e32 v[18:19], 0
	v_mov_b64_e32 v[20:21], 0
	v_mov_b64_e32 v[22:23], 0
	v_mov_b64_e32 v[24:25], 0
	v_mov_b64_e32 v[26:27], 0
	v_mov_b64_e32 v[28:29], 0
	v_mov_b64_e32 v[30:31], 0
	v_mov_b64_e32 v[32:33], 0
	v_mov_b64_e32 v[34:35], 0
	v_mov_b64_e32 v[36:37], 0
	v_mov_b64_e32 v[38:39], 0
	v_mov_b64_e32 v[40:41], 0
	v_mov_b64_e32 v[42:43], 0
	v_mov_b64_e32 v[44:45], 0
	v_mov_b64_e32 v[46:47], 0
	v_mov_b64_e32 v[48:49], 0
	v_mov_b64_e32 v[50:51], 0
	v_mov_b64_e32 v[52:53], 0
	v_mov_b64_e32 v[54:55], 0
	v_mov_b64_e32 v[56:57], 0
	v_mov_b64_e32 v[58:59], 0
	v_mov_b64_e32 v[60:61], 0
	v_mov_b64_e32 v[62:63], 0
	v_mov_b64_e32 v[64:65], 0
	v_mov_b64_e32 v[66:67], 0
	v_mov_b64_e32 v[68:69], 0
	v_mov_b64_e32 v[70:71], 0
	v_mov_b64_e32 v[72:73], 0
	v_mov_b64_e32 v[74:75], 0
	v_mov_b64_e32 v[76:77], 0
	v_mov_b64_e32 v[78:79], 0
	v_mov_b64_e32 v[80:81], 0
	v_mov_b64_e32 v[82:83], 0
	v_mov_b64_e32 v[84:85], 0
	v_mov_b64_e32 v[86:87], 0
	v_mov_b64_e32 v[88:89], 0
	v_mov_b64_e32 v[90:91], 0
	v_mov_b64_e32 v[92:93], 0
	v_mov_b64_e32 v[94:95], 0
	v_mov_b64_e32 v[96:97], 0
	v_mov_b64_e32 v[98:99], 0
	v_mov_b64_e32 v[100:101], 0
	v_mov_b64_e32 v[102:103], 0
	v_mov_b64_e32 v[104:105], 0
	v_mov_b64_e32 v[106:107], 0
	v_mov_b64_e32 v[108:109], 0
	v_mov_b64_e32 v[110:111], 0
	v_mov_b64_e32 v[112:113], 0
	v_mov_b64_e32 v[114:115], 0
	v_mov_b64_e32 v[116:117], 0
	v_mov_b64_e32 v[118:119], 0
	v_mov_b64_e32 v[120:121], 0
	v_mov_b64_e32 v[122:123], 0
	v_mov_b64_e32 v[124:125], 0
	v_mov_b64_e32 v[126:127], 0
	v_mov_b64_e32 v[128:129], 0
	s_addc_u32 s64, s41, 0
	s_mov_b32 s40, 0

;     __device__ __forceinline__ bool next(int i, Unit& u) const { const int L = i * G + c; if (L >= nM * nN * ng) return false; const int per = nM * nN, r = L % per; u.g = L / per; u.pn = r / nM; u.pm = r % nM; return true; }
; template <class Epi, class Sched, bool ALIGN_EPI = false, bool SP2 = false>
; __device__ __forceinline__ void gemm_phase(PG8_LAS unsigned char* lds, const Gemm g, const Sched& S, const Epi& E) {
;     ...
;         const bool has_next = S.next(ui + 1, nxt);
;         const char* nA = has_next ? (const char*)g.A + (size_t)nxt.g * g.gsA * 2 + (size_t)nxt.pm * tstepA : cA; const char* nB = has_next ? (const char*)g.Bt + (size_t)nxt.g * g.gsB * 2 + (size_t)nxt.pn * tstepB : cB;
;         for (int t = 0; t < nt; t += 2) {
;             const bool last = (t == nt - 2);
;             const char* a1 = cA + (size_t)(t + 1) * kstep;
;             const char* a2 = last ? nA : cA + (size_t)(t + 2) * kstep; const char* b2 = last ? nB : cB + (size_t)(t + 2) * kstep;
;             const char* a3 = a2 + kstep; const char* b3 = b2 + kstep;
;     ...
; #pragma unroll
;         for (int a = 0; a < 2; ++a)
; #pragma unroll
;             for (int b = 0; b < 2; ++b)
; #pragma unroll
;                 for (int m = 0; m < 4; ++m)
; #pragma unroll
;                     for (int n = 0; n < 2; ++n) acc[a][b][m][n] = (f32x4){0.f, 0.f, 0.f, 0.f};
.LBB0_902:
	s_ashr_i32 s29, s28, 31
	s_lshl_b64 s[0:1], s[28:29], 19
	s_add_u32 s30, s10, s0
	s_addc_u32 s31, s11, s1
	s_and_b64 s[0:1], s[8:9], exec
	s_cselect_b32 s0, s31, s37
	s_cselect_b32 s1, s30, s36
	s_ashr_i32 s27, s26, 31
	s_lshl_b64 s[34:35], s[26:27], 19
	s_add_u32 s34, s3, s34
	s_addc_u32 s35, s42, s35
	s_and_b64 s[40:41], s[8:9], exec
	s_cselect_b32 s2, s35, s39
	s_cselect_b32 s5, s34, s38
	s_add_u32 s36, s36, 0x40080
	s_addc_u32 s37, s37, 0
	s_add_u32 s27, s38, 0x100
	v_mov_b64_e32 v[2:3], 0
	v_mov_b64_e32 v[4:5], 0
	v_mov_b64_e32 v[6:7], 0
	v_mov_b64_e32 v[8:9], 0
	v_mov_b64_e32 v[10:11], 0
	v_mov_b64_e32 v[12:13], 0
	v_mov_b64_e32 v[14:15], 0
	v_mov_b64_e32 v[16:17], 0
	v_mov_b64_e32 v[18:19], 0
	v_mov_b64_e32 v[20:21], 0
	v_mov_b64_e32 v[22:23], 0
	v_mov_b64_e32 v[24:25], 0
	v_mov_b64_e32 v[26:27], 0
	v_mov_b64_e32 v[28:29], 0
	v_mov_b64_e32 v[30:31], 0
	v_mov_b64_e32 v[32:33], 0
	v_mov_b64_e32 v[34:35], 0
	v_mov_b64_e32 v[36:37], 0
	v_mov_b64_e32 v[38:39], 0
	v_mov_b64_e32 v[40:41], 0
	v_mov_b64_e32 v[42:43], 0
	v_mov_b64_e32 v[44:45], 0
	v_mov_b64_e32 v[46:47], 0
	v_mov_b64_e32 v[48:49], 0
	v_mov_b64_e32 v[50:51], 0
	v_mov_b64_e32 v[52:53], 0
	v_mov_b64_e32 v[54:55], 0
	v_mov_b64_e32 v[56:57], 0
	v_mov_b64_e32 v[58:59], 0
	v_mov_b64_e32 v[60:61], 0
	v_mov_b64_e32 v[62:63], 0
	v_mov_b64_e32 v[64:65], 0
	v_mov_b64_e32 v[66:67], 0
	v_mov_b64_e32 v[68:69], 0
	v_mov_b64_e32 v[70:71], 0
	v_mov_b64_e32 v[72:73], 0
	v_mov_b64_e32 v[74:75], 0
	v_mov_b64_e32 v[76:77], 0
	v_mov_b64_e32 v[78:79], 0
	v_mov_b64_e32 v[80:81], 0
	v_mov_b64_e32 v[82:83], 0
	v_mov_b64_e32 v[84:85], 0
	v_mov_b64_e32 v[86:87], 0
	v_mov_b64_e32 v[88:89], 0
	v_mov_b64_e32 v[90:91], 0
	v_mov_b64_e32 v[92:93], 0
	v_mov_b64_e32 v[94:95], 0
	v_mov_b64_e32 v[96:97], 0
	v_mov_b64_e32 v[98:99], 0
	v_mov_b64_e32 v[100:101], 0
	v_mov_b64_e32 v[102:103], 0
	v_mov_b64_e32 v[104:105], 0
	v_mov_b64_e32 v[106:107], 0
	v_mov_b64_e32 v[108:109], 0
	v_mov_b64_e32 v[110:111], 0
	v_mov_b64_e32 v[112:113], 0
	v_mov_b64_e32 v[114:115], 0
	v_mov_b64_e32 v[116:117], 0
	v_mov_b64_e32 v[118:119], 0
	v_mov_b64_e32 v[120:121], 0
	v_mov_b64_e32 v[122:123], 0
	v_mov_b64_e32 v[124:125], 0
	v_mov_b64_e32 v[126:127], 0
	v_mov_b64_e32 v[128:129], 0
	s_addc_u32 s29, s39, 0
	s_mov_b32 s33, -2
	s_waitcnt lgkmcnt(0)

;     __device__ __forceinline__ bool next(int i, Unit& u) const { const int L = i * G + c; if (L >= nM * nN * ng) return false; const int per = nM * nN, r = L % per; u.g = L / per; u.pn = r / nM; u.pm = r % nM; return true; }
; template <class Epi, class Sched, bool ALIGN_EPI = false, bool SP2 = false>
; __device__ __forceinline__ void gemm_phase(PG8_LAS unsigned char* lds, const Gemm g, const Sched& S, const Epi& E) {
;     ...
;         const bool has_next = S.next(ui + 1, nxt);
;         const char* nA = has_next ? (const char*)g.A + (size_t)nxt.g * g.gsA * 2 + (size_t)nxt.pm * tstepA : cA; const char* nB = has_next ? (const char*)g.Bt + (size_t)nxt.g * g.gsB * 2 + (size_t)nxt.pn * tstepB : cB;
;         for (int t = 0; t < nt; t += 2) {
;             const bool last = (t == nt - 2);
;             const char* a1 = cA + (size_t)(t + 1) * kstep;
;             const char* a2 = last ? nA : cA + (size_t)(t + 2) * kstep; const char* b2 = last ? nB : cB + (size_t)(t + 2) * kstep;
;             const char* a3 = a2 + kstep; const char* b3 = b2 + kstep;
;     ...
; #pragma unroll
;         for (int a = 0; a < 2; ++a)
; #pragma unroll
;             for (int b = 0; b < 2; ++b)
; #pragma unroll
;                 for (int m = 0; m < 4; ++m)
; #pragma unroll
;                     for (int n = 0; n < 2; ++n) acc[a][b][m][n] = (f32x4){0.f, 0.f, 0.f, 0.f};
.LBB0_988:
	s_ashr_i32 s19, s18, 31
	s_lshl_b64 s[20:21], s[18:19], 19
	s_add_u32 s20, s3, s20
	s_addc_u32 s21, s30, s21
	s_and_b64 s[22:23], s[6:7], exec
	s_cselect_b32 s1, s21, s25
	s_cselect_b32 s5, s20, s24
	s_ashr_i32 s17, s16, 31
	s_lshl_b64 s[22:23], s[16:17], 19
	s_add_u32 s22, s31, s22
	s_addc_u32 s23, s34, s23
	s_and_b64 s[28:29], s[6:7], exec
	s_cselect_b32 s17, s23, s27
	s_cselect_b32 s19, s22, s26
	s_add_u32 s24, s24, 0x40080
	s_addc_u32 s25, s25, 0
	s_add_u32 s55, s26, 0x100
	v_mov_b64_e32 v[2:3], 0
	v_mov_b64_e32 v[4:5], 0
	v_mov_b64_e32 v[6:7], 0
	v_mov_b64_e32 v[8:9], 0
	v_mov_b64_e32 v[10:11], 0
	v_mov_b64_e32 v[12:13], 0
	v_mov_b64_e32 v[14:15], 0
	v_mov_b64_e32 v[16:17], 0
	v_mov_b64_e32 v[18:19], 0
	v_mov_b64_e32 v[20:21], 0
	v_mov_b64_e32 v[22:23], 0
	v_mov_b64_e32 v[24:25], 0
	v_mov_b64_e32 v[26:27], 0
	v_mov_b64_e32 v[28:29], 0
	v_mov_b64_e32 v[30:31], 0
	v_mov_b64_e32 v[32:33], 0
	v_mov_b64_e32 v[34:35], 0
	v_mov_b64_e32 v[36:37], 0
	v_mov_b64_e32 v[38:39], 0
	v_mov_b64_e32 v[40:41], 0
	v_mov_b64_e32 v[42:43], 0
	v_mov_b64_e32 v[44:45], 0
	v_mov_b64_e32 v[46:47], 0
	v_mov_b64_e32 v[48:49], 0
	v_mov_b64_e32 v[50:51], 0
	v_mov_b64_e32 v[52:53], 0
	v_mov_b64_e32 v[54:55], 0
	v_mov_b64_e32 v[56:57], 0
	v_mov_b64_e32 v[58:59], 0
	v_mov_b64_e32 v[60:61], 0
	v_mov_b64_e32 v[62:63], 0
	v_mov_b64_e32 v[64:65], 0
	v_mov_b64_e32 v[66:67], 0
	v_mov_b64_e32 v[68:69], 0
	v_mov_b64_e32 v[70:71], 0
	v_mov_b64_e32 v[72:73], 0
	v_mov_b64_e32 v[74:75], 0
	v_mov_b64_e32 v[76:77], 0
	v_mov_b64_e32 v[78:79], 0
	v_mov_b64_e32 v[80:81], 0
	v_mov_b64_e32 v[82:83], 0
	v_mov_b64_e32 v[84:85], 0
	v_mov_b64_e32 v[86:87], 0
	v_mov_b64_e32 v[88:89], 0
	v_mov_b64_e32 v[90:91], 0
	v_mov_b64_e32 v[92:93], 0
	v_mov_b64_e32 v[94:95], 0
	v_mov_b64_e32 v[96:97], 0
	v_mov_b64_e32 v[98:99], 0
	v_mov_b64_e32 v[100:101], 0
	v_mov_b64_e32 v[102:103], 0
	v_mov_b64_e32 v[104:105], 0
	v_mov_b64_e32 v[106:107], 0
	v_mov_b64_e32 v[108:109], 0
	v_mov_b64_e32 v[110:111], 0
	v_mov_b64_e32 v[112:113], 0
	v_mov_b64_e32 v[114:115], 0
	v_mov_b64_e32 v[116:117], 0
	v_mov_b64_e32 v[118:119], 0
	v_mov_b64_e32 v[120:121], 0
	v_mov_b64_e32 v[122:123], 0
	v_mov_b64_e32 v[124:125], 0
	v_mov_b64_e32 v[126:127], 0
	v_mov_b64_e32 v[128:129], 0
	s_addc_u32 s56, s27, 0
	s_mov_b32 s57, -2

;     __device__ __forceinline__ bool next(int i, Unit& u) const { const int L = i * G + c; if (L >= nM * nN * ng) return false; const int per = nM * nN, r = L % per; u.g = L / per; u.pn = r / nM; u.pm = r % nM; return true; }
; template <class Epi, class Sched, bool ALIGN_EPI = false, bool SP2 = false>
; __device__ __forceinline__ void gemm_phase(PG8_LAS unsigned char* lds, const Gemm g, const Sched& S, const Epi& E) {
;     ...
;         const bool has_next = S.next(ui + 1, nxt);
;         const char* nA = has_next ? (const char*)g.A + (size_t)nxt.g * g.gsA * 2 + (size_t)nxt.pm * tstepA : cA; const char* nB = has_next ? (const char*)g.Bt + (size_t)nxt.g * g.gsB * 2 + (size_t)nxt.pn * tstepB : cB;
;         for (int t = 0; t < nt; t += 2) {
;             const bool last = (t == nt - 2);
;             const char* a1 = cA + (size_t)(t + 1) * kstep;
;             const char* a2 = last ? nA : cA + (size_t)(t + 2) * kstep; const char* b2 = last ? nB : cB + (size_t)(t + 2) * kstep;
;             const char* a3 = a2 + kstep; const char* b3 = b2 + kstep;
;     ...
; #pragma unroll
;         for (int a = 0; a < 2; ++a)
; #pragma unroll
;             for (int b = 0; b < 2; ++b)
; #pragma unroll
;                 for (int m = 0; m < 4; ++m)
; #pragma unroll
;                     for (int n = 0; n < 2; ++n) acc[a][b][m][n] = (f32x4){0.f, 0.f, 0.f, 0.f};
.LBB0_1466:
	s_ashr_i32 s23, s22, 31
	s_lshl_b64 s[24:25], s[22:23], 19
	s_add_u32 s24, s2, s24
	s_addc_u32 s25, s3, s25
	s_and_b64 s[26:27], s[8:9], exec
	s_cselect_b32 s23, s25, s31
	s_cselect_b32 s29, s24, s30
	s_ashr_i32 s21, s20, 31
	s_lshl_b64 s[26:27], s[20:21], 19
	s_add_u32 s26, s33, s26
	s_addc_u32 s27, s38, s27
	s_and_b64 s[36:37], s[8:9], exec
	s_cselect_b32 s21, s27, s35
	s_cselect_b32 s51, s26, s34
	s_add_u32 s30, s30, 0x40080
	s_addc_u32 s31, s31, 0
	s_add_u32 s52, s34, 0x100
	v_mov_b64_e32 v[2:3], 0
	v_mov_b64_e32 v[4:5], 0
	v_mov_b64_e32 v[6:7], 0
	v_mov_b64_e32 v[8:9], 0
	v_mov_b64_e32 v[10:11], 0
	v_mov_b64_e32 v[12:13], 0
	v_mov_b64_e32 v[14:15], 0
	v_mov_b64_e32 v[16:17], 0
	v_mov_b64_e32 v[18:19], 0
	v_mov_b64_e32 v[20:21], 0
	v_mov_b64_e32 v[22:23], 0
	v_mov_b64_e32 v[24:25], 0
	v_mov_b64_e32 v[26:27], 0
	v_mov_b64_e32 v[28:29], 0
	v_mov_b64_e32 v[30:31], 0
	v_mov_b64_e32 v[32:33], 0
	v_mov_b64_e32 v[34:35], 0
	v_mov_b64_e32 v[36:37], 0
	v_mov_b64_e32 v[38:39], 0
	v_mov_b64_e32 v[40:41], 0
	v_mov_b64_e32 v[42:43], 0
	v_mov_b64_e32 v[44:45], 0
	v_mov_b64_e32 v[46:47], 0
	v_mov_b64_e32 v[48:49], 0
	v_mov_b64_e32 v[50:51], 0
	v_mov_b64_e32 v[52:53], 0
	v_mov_b64_e32 v[54:55], 0
	v_mov_b64_e32 v[56:57], 0
	v_mov_b64_e32 v[58:59], 0
	v_mov_b64_e32 v[60:61], 0
	v_mov_b64_e32 v[62:63], 0
	v_mov_b64_e32 v[64:65], 0
	v_mov_b64_e32 v[66:67], 0
	v_mov_b64_e32 v[68:69], 0
	v_mov_b64_e32 v[70:71], 0
	v_mov_b64_e32 v[72:73], 0
	v_mov_b64_e32 v[74:75], 0
	v_mov_b64_e32 v[76:77], 0
	v_mov_b64_e32 v[78:79], 0
	v_mov_b64_e32 v[80:81], 0
	v_mov_b64_e32 v[82:83], 0
	v_mov_b64_e32 v[84:85], 0
	v_mov_b64_e32 v[86:87], 0
	v_mov_b64_e32 v[88:89], 0
	v_mov_b64_e32 v[90:91], 0
	v_mov_b64_e32 v[92:93], 0
	v_mov_b64_e32 v[94:95], 0
	v_mov_b64_e32 v[96:97], 0
	v_mov_b64_e32 v[98:99], 0
	v_mov_b64_e32 v[100:101], 0
	v_mov_b64_e32 v[102:103], 0
	v_mov_b64_e32 v[104:105], 0
	v_mov_b64_e32 v[106:107], 0
	v_mov_b64_e32 v[108:109], 0
	v_mov_b64_e32 v[110:111], 0
	v_mov_b64_e32 v[112:113], 0
	v_mov_b64_e32 v[114:115], 0
	v_mov_b64_e32 v[116:117], 0
	v_mov_b64_e32 v[118:119], 0
	v_mov_b64_e32 v[120:121], 0
	v_mov_b64_e32 v[122:123], 0
	v_mov_b64_e32 v[124:125], 0
	v_mov_b64_e32 v[126:127], 0
	v_mov_b64_e32 v[128:129], 0
	s_addc_u32 s53, s35, 0
	s_mov_b32 s54, -2
	s_waitcnt lgkmcnt(0)
